# phase B: first 24 fragment loads of the sample-row split-K GEMM issued at the start of the block's last main-tile epilogue (memory idle there); tail issues the remaining 12
# speedup vs baseline: 1.0036x; 1.0036x over previous
; __device__ __forceinline__ u32x2 pack4(f32x4 v) { u32x2 r; r.x = cvt_pk(v[0], v[1]); r.y = cvt_pk(v[2], v[3]); return r; }
; __device__ __forceinline__ float sigm_f(float x) { return __builtin_amdgcn_rcpf(1.f + __builtin_amdgcn_exp2f(-1.4426950409f * x)); }
; template <int SEC> __device__ __forceinline__ void epiB2(const Params& p, int row, int col32, f32x4 v0, f32x4 v1, int fq) {
;     ...
;   else { f32x4 o0 = {sigm_f(v0[0]), sigm_f(v0[1]), sigm_f(v0[2]), sigm_f(v0[3])}, o1 = {sigm_f(v1[0]), sigm_f(v1[1]), sigm_f(v1[2]), sigm_f(v1[3])};
;     store_pair16((u16*)(ws + OFF_GATE) + (size_t)row * 3072 + (col32 - 4096), pack4(o0), pack4(o1), fq); }
; __device__ __forceinline__ void phaseB(const Params& p, const int wv, const int rep) {
;     ...
;       switch (sec) {
;         case 0: ACC_FOREACH_PAIR({ epiB2<0>(p, brow + rrow, bcol + cb32, v0, v1, fq); }); break;
;         case 1: ACC_FOREACH_PAIR({ epiB2<1>(p, brow + rrow, bcol + cb32, v0, v1, fq); }); break;
;         case 2: ACC_FOREACH_PAIR({ epiB2<2>(p, brow + rrow, bcol + cb32, v0, v1, fq); }); break;
;         case 3: ACC_FOREACH_PAIR({ epiB2<3>(p, brow + rrow, bcol + cb32, v0, v1, fq); }); break;
;         default: ACC_FOREACH_PAIR({ epiB2<4>(p, brow + rrow, bcol + cb32, v0, v1, fq); }); break;
;       }
;     }
;   }
;   for (int gb = blockIdx.x; gb < 256; gb += gridDim.x) {
;     const int task0 = gb * 14, mt = task0 / 448, nt0 = task0 - mt * 448;
;     const u16* Ab = XN + (size_t)(TP + mt * 16) * 1024;
;     const u16* Bb = (const u16*)(ws + OFF_WIN) + (size_t)(nt0 * 16) * 1024;
;     skgemm<14>([&](int) { return Ab; }, [&](int i) { return Bb + (size_t)i * 16 * 1024; }, [&](int) { return 1024; }, 128, wv);
.LBB0_198:
	s_add_i32 s33, s33, s57
	s_cmpk_lt_u32 s52, 0x1000
	s_cselect_b32 s4, 3, 4
	s_cmpk_gt_u32 s52, 0xdff
	s_cselect_b32 s4, s4, 2
	s_cmpk_gt_u32 s52, 0x7ff
	s_cselect_b32 s4, s4, 1
	s_cmpk_gt_i32 s38, 0x3ff
	s_cselect_b32 s39, s4, 0
	s_cmp_lt_i32 s39, 2
	s_mov_b64 s[4:5], -1
	s_cbranch_scc1 .LBB0_216
	s_cmp_lt_i32 s39, 3
	s_cbranch_scc1 .LBB0_205
	s_cmp_lg_u32 s39, 3
	s_cbranch_scc0 .LBB0_202
	s_and_b64 vcc, exec, s[36:37]
	s_cbranch_vccz .Lbh_skip
	v_readlane_b32 s98, v251, 1
	s_cmp_lg_u32 s98, 0x100
	s_cbranch_scc1 .Lbh_skip
	v_readlane_b32 s98, v251, 0
	s_nop 3
	s_and_b32 s100, s98, 63
	s_mul_i32 s100, s100, 7
	s_lshl_b32 s100, s100, 15
	s_add_u32 s100, s50, s100
	s_addc_u32 s101, s51, 0
	s_lshr_b32 s98, s98, 6
	s_lshl_b32 s98, s98, 5
	s_addk_i32 s98, 0x4000
	s_lshl_b32 s98, s98, 11
	s_add_u32 s98, s48, s98
	s_addc_u32 s99, s49, 0
	v_mbcnt_lo_u32_b32 v246, -1, 0
	v_mbcnt_hi_u32_b32 v246, -1, v246
	v_and_b32_e32 v248, 15, v246
	v_lshlrev_b32_e32 v248, 11, v248
	v_lshrrev_b32_e32 v246, 4, v246
	v_lshl_add_u32 v248, v246, 4, v248
	s_lshl_b32 s4, s83, 8
	v_add_u32_e32 v248, s4, v248
	global_load_dwordx4 v[150:153], v248, s[98:99]
	global_load_dwordx4 v[154:157], v248, s[98:99] offset:64
	global_load_dwordx4 v[158:161], v248, s[98:99] offset:128
	global_load_dwordx4 v[162:165], v248, s[98:99] offset:192
	s_add_u32 s98, s98, 0x8000
	s_addc_u32 s99, s99, 0
	global_load_dwordx4 v[166:169], v248, s[98:99]
	global_load_dwordx4 v[170:173], v248, s[98:99] offset:64
	global_load_dwordx4 v[174:177], v248, s[98:99] offset:128
	global_load_dwordx4 v[178:181], v248, s[98:99] offset:192
	global_load_dwordx4 v[182:185], v248, s[100:101]
	global_load_dwordx4 v[186:189], v248, s[100:101] offset:64
	global_load_dwordx4 v[190:193], v248, s[100:101] offset:128
	global_load_dwordx4 v[194:197], v248, s[100:101] offset:192
	s_add_u32 s100, s100, 0x8000
	s_addc_u32 s101, s101, 0
	global_load_dwordx4 v[198:201], v248, s[100:101]
	global_load_dwordx4 v[202:205], v248, s[100:101] offset:64
	global_load_dwordx4 v[206:209], v248, s[100:101] offset:128
	global_load_dwordx4 v[210:213], v248, s[100:101] offset:192
	s_add_u32 s100, s100, 0x8000
	s_addc_u32 s101, s101, 0
	global_load_dwordx4 v[214:217], v248, s[100:101]
	global_load_dwordx4 v[218:221], v248, s[100:101] offset:64
	global_load_dwordx4 v[222:225], v248, s[100:101] offset:128
	global_load_dwordx4 v[226:229], v248, s[100:101] offset:192
	s_add_u32 s100, s100, 0x8000
	s_addc_u32 s101, s101, 0
	global_load_dwordx4 v[230:233], v248, s[100:101]
	global_load_dwordx4 v[234:237], v248, s[100:101] offset:64
	global_load_dwordx4 v[238:241], v248, s[100:101] offset:128
	global_load_dwordx4 v[242:245], v248, s[100:101] offset:192
	s_add_u32 s100, s100, 0x8000
	s_addc_u32 s101, s101, 0
	s_mov_b64 s[4:5], -1
.Lbh_skip:
	v_mbcnt_lo_u32_b32 v130, -1, 0
	v_mbcnt_hi_u32_b32 v130, -1, v130
	v_mul_f32_e32 v134, 0xbfb8aa3b, v127
	v_and_or_b32 v128, v130, 15, s33
	v_and_b32_e32 v131, 16, v130
	v_ashrrev_i32_e32 v130, 2, v130
	v_and_b32_e32 v130, -8, v130
	v_add_u32_e32 v132, v130, v131
	v_mul_f32_e32 v130, 0xbfb8aa3b, v124
	v_exp_f32_e32 v130, v130
	v_mul_f32_e32 v131, 0xbfb8aa3b, v125
	v_exp_f32_e32 v131, v131
	v_exp_f32_e32 v134, v134
	v_add_f32_e32 v130, 1.0, v130
	v_rcp_f32_e32 v137, v130
	v_add_f32_e32 v130, 1.0, v131
	v_mul_f32_e32 v131, 0xbfb8aa3b, v126
	v_exp_f32_e32 v131, v131
	v_rcp_f32_e32 v138, v130
	s_or_b32 s4, s38, s66
	s_ashr_i32 s5, s4, 31
	v_add_f32_e32 v130, 1.0, v131
	v_mul_f32_e32 v131, 0xbfb8aa3b, v120
	v_rcp_f32_e32 v139, v130
	v_add_f32_e32 v130, 1.0, v134
	v_exp_f32_e32 v131, v131
	v_mul_f32_e32 v134, 0xbfb8aa3b, v121
	v_exp_f32_e32 v134, v134
	v_rcp_f32_e32 v140, v130
	v_add_f32_e32 v130, 1.0, v131
	v_mul_f32_e32 v131, 0xbfb8aa3b, v122
	v_rcp_f32_e32 v141, v130
	v_add_f32_e32 v130, 1.0, v134
	v_exp_f32_e32 v131, v131
	v_mul_f32_e32 v134, 0xbfb8aa3b, v123
	v_exp_f32_e32 v134, v134
	v_rcp_f32_e32 v142, v130
	v_add_f32_e32 v130, 1.0, v131
	v_rcp_f32_e32 v143, v130
	v_add_f32_e32 v130, 1.0, v134
	v_rcp_f32_e32 v144, v130
	v_mov_b64_e32 v[130:131], s[50:51]
	v_ashrrev_i32_e32 v133, 31, v132
	v_mad_u64_u32 v[134:135], s[40:41], v128, s71, v[130:131]
	s_lshl_b64 s[4:5], s[4:5], 1
	v_cvt_pk_bf16_f32 v139, v139, v140
	v_cvt_pk_bf16_f32 v140, v141, v142
	v_mul_f32_e32 v142, 0xbfb8aa3b, v117
	v_lshl_add_u64 v[134:135], v[134:135], 0, s[4:5]
	v_lshlrev_b64 v[132:133], 1, v[132:133]
	v_exp_f32_e32 v142, v142
	v_lshl_add_u64 v[134:135], v[134:135], 0, v[132:133]
	v_cvt_pk_bf16_f32 v138, v137, v138
	v_cvt_pk_bf16_f32 v141, v143, v144
	v_add_co_u32_e32 v134, vcc, s72, v134
	v_permlane16_swap_b32_e32 v138, v140
	v_permlane16_swap_b32_e32 v139, v141
	v_addc_co_u32_e32 v135, vcc, 0, v135, vcc
	v_mul_f32_e32 v137, 0xbfb8aa3b, v116
	global_store_dwordx4 v[134:135], v[138:141], off
	v_mul_f32_e32 v143, 0xbfb8aa3b, v114
	v_mul_f32_e32 v144, 0xbfb8aa3b, v115
	v_add_f32_e32 v138, 1.0, v142
	v_mul_f32_e32 v139, 0xbfb8aa3b, v118
	v_mul_f32_e32 v140, 0xbfb8aa3b, v119
	v_mul_f32_e32 v141, 0xbfb8aa3b, v112
	v_mul_f32_e32 v142, 0xbfb8aa3b, v113
	v_exp_f32_e32 v137, v137
	v_exp_f32_e32 v139, v139
	v_exp_f32_e32 v140, v140
	v_exp_f32_e32 v141, v141
	v_exp_f32_e32 v142, v142
	v_exp_f32_e32 v143, v143
	v_exp_f32_e32 v144, v144
	v_add_f32_e32 v137, 1.0, v137
	v_add_f32_e32 v139, 1.0, v139
	v_add_f32_e32 v140, 1.0, v140
	v_add_f32_e32 v141, 1.0, v141
	v_add_f32_e32 v142, 1.0, v142
	v_add_f32_e32 v143, 1.0, v143
	v_add_f32_e32 v144, 1.0, v144
	v_rcp_f32_e32 v137, v137
	v_rcp_f32_e32 v138, v138
	v_rcp_f32_e32 v139, v139
	v_rcp_f32_e32 v140, v140
	v_rcp_f32_e32 v141, v141
	v_rcp_f32_e32 v142, v142
	v_rcp_f32_e32 v143, v143
; __device__ __forceinline__ u32x2 pack4(f32x4 v) { u32x2 r; r.x = cvt_pk(v[0], v[1]); r.y = cvt_pk(v[2], v[3]); return r; }
; __device__ __forceinline__ float sigm_f(float x) { return __builtin_amdgcn_rcpf(1.f + __builtin_amdgcn_exp2f(-1.4426950409f * x)); }
; __device__ __forceinline__ void store_pair16(u16* rowp32, u32x2 a, u32x2 b, int fq) {
;   auto rx = __builtin_amdgcn_permlane16_swap(a.x, b.x, false, false);
;   auto ry = __builtin_amdgcn_permlane16_swap(a.y, b.y, false, false);
;   u32x4 w = {rx[0], ry[0], rx[1], ry[1]};
;   *(u32x4*)(rowp32 + ((fq & 1) * 16 + (fq >> 1) * 8)) = w;
; template <int SEC> __device__ __forceinline__ void epiB2(const Params& p, int row, int col32, f32x4 v0, f32x4 v1, int fq) {
;     ...
;   else { f32x4 o0 = {sigm_f(v0[0]), sigm_f(v0[1]), sigm_f(v0[2]), sigm_f(v0[3])}, o1 = {sigm_f(v1[0]), sigm_f(v1[1]), sigm_f(v1[2]), sigm_f(v1[3])};
;     store_pair16((u16*)(ws + OFF_GATE) + (size_t)row * 3072 + (col32 - 4096), pack4(o0), pack4(o1), fq); }
	v_rcp_f32_e32 v144, v144
	v_cvt_pk_bf16_f32 v138, v137, v138
	v_cvt_pk_bf16_f32 v139, v139, v140
	v_cvt_pk_bf16_f32 v140, v141, v142
	v_cvt_pk_bf16_f32 v141, v143, v144
	s_nop 0
	v_permlane16_swap_b32_e32 v138, v140
	v_permlane16_swap_b32_e32 v139, v141
	global_store_dwordx4 v[134:135], v[138:141], off offset:256
	v_mul_f32_e32 v134, 0xbfb8aa3b, v108
	v_exp_f32_e32 v134, v134
	v_mul_f32_e32 v135, 0xbfb8aa3b, v109
	v_exp_f32_e32 v135, v135
	v_mul_f32_e32 v139, 0xbfb8aa3b, v111
	v_add_f32_e32 v134, 1.0, v134
	v_rcp_f32_e32 v138, v134
	v_add_f32_e32 v134, 1.0, v135
	v_mul_f32_e32 v135, 0xbfb8aa3b, v110
	v_exp_f32_e32 v135, v135
	v_exp_f32_e32 v139, v139
	v_rcp_f32_e32 v140, v134
	v_or_b32_e32 v137, 16, v128
	v_add_f32_e32 v134, 1.0, v135
	v_mul_f32_e32 v135, 0xbfb8aa3b, v104
	v_rcp_f32_e32 v141, v134
	v_add_f32_e32 v134, 1.0, v139
	v_exp_f32_e32 v135, v135
	v_mul_f32_e32 v139, 0xbfb8aa3b, v105
	v_exp_f32_e32 v139, v139
	v_rcp_f32_e32 v142, v134
	v_add_f32_e32 v134, 1.0, v135
	v_mul_f32_e32 v135, 0xbfb8aa3b, v106
	v_rcp_f32_e32 v143, v134
	v_add_f32_e32 v134, 1.0, v139
	v_exp_f32_e32 v135, v135
	v_mul_f32_e32 v139, 0xbfb8aa3b, v107
	v_exp_f32_e32 v139, v139
	v_rcp_f32_e32 v144, v134
	v_add_f32_e32 v134, 1.0, v135
	v_rcp_f32_e32 v145, v134
	v_add_f32_e32 v134, 1.0, v139
	v_rcp_f32_e32 v146, v134
	v_mad_u64_u32 v[134:135], s[40:41], v137, s71, v[130:131]
	v_cvt_pk_bf16_f32 v139, v141, v142
	v_mul_f32_e32 v142, 0xbfb8aa3b, v101
	v_lshl_add_u64 v[134:135], v[134:135], 0, s[4:5]
	v_exp_f32_e32 v142, v142
	v_lshl_add_u64 v[134:135], v[134:135], 0, v[132:133]
	v_cvt_pk_bf16_f32 v138, v138, v140
	v_cvt_pk_bf16_f32 v140, v143, v144
	v_cvt_pk_bf16_f32 v141, v145, v146
	v_add_co_u32_e32 v134, vcc, s72, v134
	v_permlane16_swap_b32_e32 v138, v140
	v_permlane16_swap_b32_e32 v139, v141
	v_addc_co_u32_e32 v135, vcc, 0, v135, vcc
	v_mul_f32_e32 v137, 0xbfb8aa3b, v100
	global_store_dwordx4 v[134:135], v[138:141], off
	v_mul_f32_e32 v143, 0xbfb8aa3b, v98
	v_mul_f32_e32 v144, 0xbfb8aa3b, v99
	v_add_f32_e32 v138, 1.0, v142
	v_mul_f32_e32 v139, 0xbfb8aa3b, v102
	v_mul_f32_e32 v140, 0xbfb8aa3b, v103
	v_mul_f32_e32 v141, 0xbfb8aa3b, v96
	v_mul_f32_e32 v142, 0xbfb8aa3b, v97
	v_exp_f32_e32 v137, v137
	v_exp_f32_e32 v139, v139
	v_exp_f32_e32 v140, v140
	v_exp_f32_e32 v141, v141
	v_exp_f32_e32 v142, v142
	v_exp_f32_e32 v143, v143
	v_exp_f32_e32 v144, v144
	v_add_f32_e32 v137, 1.0, v137
	v_add_f32_e32 v139, 1.0, v139
	v_add_f32_e32 v140, 1.0, v140
	v_add_f32_e32 v141, 1.0, v141
	v_add_f32_e32 v142, 1.0, v142
	v_add_f32_e32 v143, 1.0, v143
	v_add_f32_e32 v144, 1.0, v144
	v_rcp_f32_e32 v137, v137
	v_rcp_f32_e32 v138, v138
	v_rcp_f32_e32 v139, v139
	v_rcp_f32_e32 v140, v140
	v_rcp_f32_e32 v141, v141
	v_rcp_f32_e32 v142, v142
	v_rcp_f32_e32 v143, v143
	v_rcp_f32_e32 v144, v144
	v_cvt_pk_bf16_f32 v138, v137, v138
	v_cvt_pk_bf16_f32 v139, v139, v140
	v_cvt_pk_bf16_f32 v140, v141, v142
	v_cvt_pk_bf16_f32 v141, v143, v144
	s_nop 0
	v_permlane16_swap_b32_e32 v138, v140
	v_permlane16_swap_b32_e32 v139, v141
	global_store_dwordx4 v[134:135], v[138:141], off offset:256
	v_mul_f32_e32 v134, 0xbfb8aa3b, v92
	v_exp_f32_e32 v134, v134
	v_mul_f32_e32 v135, 0xbfb8aa3b, v93
	v_exp_f32_e32 v135, v135
	v_mul_f32_e32 v139, 0xbfb8aa3b, v95
	v_add_f32_e32 v134, 1.0, v134
	v_rcp_f32_e32 v138, v134
	v_add_f32_e32 v134, 1.0, v135
	v_mul_f32_e32 v135, 0xbfb8aa3b, v94
	v_exp_f32_e32 v135, v135
	v_exp_f32_e32 v139, v139
	v_rcp_f32_e32 v140, v134
	v_or_b32_e32 v137, 32, v128
	v_add_f32_e32 v134, 1.0, v135
	v_mul_f32_e32 v135, 0xbfb8aa3b, v88
	v_rcp_f32_e32 v141, v134
	v_add_f32_e32 v134, 1.0, v139
	v_exp_f32_e32 v135, v135
	v_mul_f32_e32 v139, 0xbfb8aa3b, v89
	v_exp_f32_e32 v139, v139
	v_rcp_f32_e32 v142, v134
	v_add_f32_e32 v134, 1.0, v135
	v_mul_f32_e32 v135, 0xbfb8aa3b, v90
	v_rcp_f32_e32 v143, v134
	v_add_f32_e32 v134, 1.0, v139
	v_exp_f32_e32 v135, v135
	v_mul_f32_e32 v139, 0xbfb8aa3b, v91
	v_exp_f32_e32 v139, v139
	v_rcp_f32_e32 v144, v134
	v_add_f32_e32 v134, 1.0, v135
	v_rcp_f32_e32 v145, v134
	v_add_f32_e32 v134, 1.0, v139
	v_rcp_f32_e32 v146, v134
	v_mad_u64_u32 v[134:135], s[40:41], v137, s71, v[130:131]
	v_cvt_pk_bf16_f32 v139, v141, v142
	v_mul_f32_e32 v142, 0xbfb8aa3b, v85
	v_lshl_add_u64 v[134:135], v[134:135], 0, s[4:5]
	v_exp_f32_e32 v142, v142
	v_lshl_add_u64 v[134:135], v[134:135], 0, v[132:133]
	v_cvt_pk_bf16_f32 v138, v138, v140
	v_cvt_pk_bf16_f32 v140, v143, v144
	v_cvt_pk_bf16_f32 v141, v145, v146
	v_add_co_u32_e32 v134, vcc, s72, v134
	v_permlane16_swap_b32_e32 v138, v140
	v_permlane16_swap_b32_e32 v139, v141
	v_addc_co_u32_e32 v135, vcc, 0, v135, vcc
	v_mul_f32_e32 v137, 0xbfb8aa3b, v84
	global_store_dwordx4 v[134:135], v[138:141], off
	v_mul_f32_e32 v143, 0xbfb8aa3b, v82
	v_mul_f32_e32 v144, 0xbfb8aa3b, v83
	v_add_f32_e32 v138, 1.0, v142
	v_mul_f32_e32 v139, 0xbfb8aa3b, v86
	v_mul_f32_e32 v140, 0xbfb8aa3b, v87
	v_mul_f32_e32 v141, 0xbfb8aa3b, v80
	v_mul_f32_e32 v142, 0xbfb8aa3b, v81
	v_exp_f32_e32 v137, v137
	v_exp_f32_e32 v139, v139
	v_exp_f32_e32 v140, v140
	v_exp_f32_e32 v141, v141
	v_exp_f32_e32 v142, v142
	v_exp_f32_e32 v143, v143
	v_exp_f32_e32 v144, v144
	v_add_f32_e32 v137, 1.0, v137
	v_add_f32_e32 v139, 1.0, v139
	v_add_f32_e32 v140, 1.0, v140
	v_add_f32_e32 v141, 1.0, v141
	v_add_f32_e32 v142, 1.0, v142
	v_add_f32_e32 v143, 1.0, v143
	v_add_f32_e32 v144, 1.0, v144
	v_rcp_f32_e32 v137, v137
	v_rcp_f32_e32 v138, v138
	v_rcp_f32_e32 v139, v139
	v_rcp_f32_e32 v140, v140
	v_rcp_f32_e32 v141, v141
	v_rcp_f32_e32 v142, v142
	v_rcp_f32_e32 v143, v143
	v_rcp_f32_e32 v144, v144
	v_cvt_pk_bf16_f32 v138, v137, v138
	v_cvt_pk_bf16_f32 v139, v139, v140
	v_cvt_pk_bf16_f32 v140, v141, v142
; __device__ __forceinline__ u32x2 pack4(f32x4 v) { u32x2 r; r.x = cvt_pk(v[0], v[1]); r.y = cvt_pk(v[2], v[3]); return r; }
; __device__ __forceinline__ float sigm_f(float x) { return __builtin_amdgcn_rcpf(1.f + __builtin_amdgcn_exp2f(-1.4426950409f * x)); }
; __device__ __forceinline__ void store_pair16(u16* rowp32, u32x2 a, u32x2 b, int fq) {
;   auto rx = __builtin_amdgcn_permlane16_swap(a.x, b.x, false, false);
;   auto ry = __builtin_amdgcn_permlane16_swap(a.y, b.y, false, false);
;   u32x4 w = {rx[0], ry[0], rx[1], ry[1]};
;   *(u32x4*)(rowp32 + ((fq & 1) * 16 + (fq >> 1) * 8)) = w;
; template <int SEC> __device__ __forceinline__ void epiB2(const Params& p, int row, int col32, f32x4 v0, f32x4 v1, int fq) {
;     ...
;   else { f32x4 o0 = {sigm_f(v0[0]), sigm_f(v0[1]), sigm_f(v0[2]), sigm_f(v0[3])}, o1 = {sigm_f(v1[0]), sigm_f(v1[1]), sigm_f(v1[2]), sigm_f(v1[3])};
;     store_pair16((u16*)(ws + OFF_GATE) + (size_t)row * 3072 + (col32 - 4096), pack4(o0), pack4(o1), fq); }
	v_cvt_pk_bf16_f32 v141, v143, v144
	s_nop 0
	v_permlane16_swap_b32_e32 v138, v140
	v_permlane16_swap_b32_e32 v139, v141
	global_store_dwordx4 v[134:135], v[138:141], off offset:256
	v_mul_f32_e32 v134, 0xbfb8aa3b, v76
	v_exp_f32_e32 v134, v134
	v_mul_f32_e32 v135, 0xbfb8aa3b, v77
	v_exp_f32_e32 v135, v135
	v_mul_f32_e32 v139, 0xbfb8aa3b, v79
	v_add_f32_e32 v134, 1.0, v134
	v_rcp_f32_e32 v138, v134
	v_add_f32_e32 v134, 1.0, v135
	v_mul_f32_e32 v135, 0xbfb8aa3b, v78
	v_exp_f32_e32 v135, v135
	v_exp_f32_e32 v139, v139
	v_rcp_f32_e32 v140, v134
	v_or_b32_e32 v137, 48, v128
	v_add_f32_e32 v134, 1.0, v135
	v_mul_f32_e32 v135, 0xbfb8aa3b, v72
	v_rcp_f32_e32 v141, v134
	v_add_f32_e32 v134, 1.0, v139
	v_exp_f32_e32 v135, v135
	v_mul_f32_e32 v139, 0xbfb8aa3b, v73
	v_exp_f32_e32 v139, v139
	v_rcp_f32_e32 v142, v134
	v_add_f32_e32 v134, 1.0, v135
	v_mul_f32_e32 v135, 0xbfb8aa3b, v74
	v_rcp_f32_e32 v143, v134
	v_add_f32_e32 v134, 1.0, v139
	v_exp_f32_e32 v135, v135
	v_mul_f32_e32 v139, 0xbfb8aa3b, v75
	v_exp_f32_e32 v139, v139
	v_rcp_f32_e32 v144, v134
	v_add_f32_e32 v134, 1.0, v135
	v_rcp_f32_e32 v145, v134
	v_add_f32_e32 v134, 1.0, v139
	v_rcp_f32_e32 v146, v134
	v_mad_u64_u32 v[134:135], s[40:41], v137, s71, v[130:131]
	v_cvt_pk_bf16_f32 v139, v141, v142
	v_mul_f32_e32 v142, 0xbfb8aa3b, v69
	v_lshl_add_u64 v[134:135], v[134:135], 0, s[4:5]
	v_exp_f32_e32 v142, v142
	v_lshl_add_u64 v[134:135], v[134:135], 0, v[132:133]
	v_cvt_pk_bf16_f32 v138, v138, v140
	v_cvt_pk_bf16_f32 v140, v143, v144
	v_cvt_pk_bf16_f32 v141, v145, v146
	v_add_co_u32_e32 v134, vcc, s72, v134
	v_permlane16_swap_b32_e32 v138, v140
	v_permlane16_swap_b32_e32 v139, v141
	v_addc_co_u32_e32 v135, vcc, 0, v135, vcc
	v_mul_f32_e32 v137, 0xbfb8aa3b, v68
	global_store_dwordx4 v[134:135], v[138:141], off
	v_mul_f32_e32 v143, 0xbfb8aa3b, v66
	v_mul_f32_e32 v144, 0xbfb8aa3b, v67
	v_add_f32_e32 v138, 1.0, v142
	v_mul_f32_e32 v139, 0xbfb8aa3b, v70
	v_mul_f32_e32 v140, 0xbfb8aa3b, v71
	v_mul_f32_e32 v141, 0xbfb8aa3b, v64
	v_mul_f32_e32 v142, 0xbfb8aa3b, v65
	v_exp_f32_e32 v137, v137
	v_exp_f32_e32 v139, v139
	v_exp_f32_e32 v140, v140
	v_exp_f32_e32 v141, v141
	v_exp_f32_e32 v142, v142
	v_exp_f32_e32 v143, v143
	v_exp_f32_e32 v144, v144
	v_add_f32_e32 v137, 1.0, v137
	v_add_f32_e32 v139, 1.0, v139
	v_add_f32_e32 v140, 1.0, v140
	v_add_f32_e32 v141, 1.0, v141
	v_add_f32_e32 v142, 1.0, v142
	v_add_f32_e32 v143, 1.0, v143
	v_add_f32_e32 v144, 1.0, v144
	v_rcp_f32_e32 v137, v137
	v_rcp_f32_e32 v138, v138
	v_rcp_f32_e32 v139, v139
	v_rcp_f32_e32 v140, v140
	v_rcp_f32_e32 v141, v141
	v_rcp_f32_e32 v142, v142
	v_rcp_f32_e32 v143, v143
	v_rcp_f32_e32 v144, v144
	v_cvt_pk_bf16_f32 v138, v137, v138
	v_cvt_pk_bf16_f32 v139, v139, v140
	v_cvt_pk_bf16_f32 v140, v141, v142
	v_cvt_pk_bf16_f32 v141, v143, v144
	s_nop 0
	v_permlane16_swap_b32_e32 v138, v140
	v_permlane16_swap_b32_e32 v139, v141
	global_store_dwordx4 v[134:135], v[138:141], off offset:256
	v_mul_f32_e32 v134, 0xbfb8aa3b, v60
	v_exp_f32_e32 v134, v134
	v_mul_f32_e32 v135, 0xbfb8aa3b, v61
	v_exp_f32_e32 v135, v135
	v_mul_f32_e32 v139, 0xbfb8aa3b, v63
	v_add_f32_e32 v134, 1.0, v134
	v_rcp_f32_e32 v138, v134
	v_add_f32_e32 v134, 1.0, v135
	v_mul_f32_e32 v135, 0xbfb8aa3b, v62
	v_exp_f32_e32 v135, v135
	v_exp_f32_e32 v139, v139
	v_rcp_f32_e32 v140, v134
	v_add_u32_e32 v137, 0x80, v128
	v_add_f32_e32 v134, 1.0, v135
	v_mul_f32_e32 v135, 0xbfb8aa3b, v56
	v_rcp_f32_e32 v141, v134
	v_add_f32_e32 v134, 1.0, v139
	v_exp_f32_e32 v135, v135
	v_mul_f32_e32 v139, 0xbfb8aa3b, v57
	v_exp_f32_e32 v139, v139
	v_rcp_f32_e32 v142, v134
	v_add_f32_e32 v134, 1.0, v135
	v_mul_f32_e32 v135, 0xbfb8aa3b, v58
	v_rcp_f32_e32 v143, v134
	v_add_f32_e32 v134, 1.0, v139
	v_exp_f32_e32 v135, v135
	v_mul_f32_e32 v139, 0xbfb8aa3b, v59
	v_exp_f32_e32 v139, v139
	v_rcp_f32_e32 v144, v134
	v_add_f32_e32 v134, 1.0, v135
	v_rcp_f32_e32 v145, v134
	v_add_f32_e32 v134, 1.0, v139
	v_rcp_f32_e32 v146, v134
	v_mad_u64_u32 v[134:135], s[40:41], v137, s71, v[130:131]
	v_cvt_pk_bf16_f32 v139, v141, v142
	v_mul_f32_e32 v142, 0xbfb8aa3b, v53
	v_lshl_add_u64 v[134:135], v[134:135], 0, s[4:5]
	v_exp_f32_e32 v142, v142
	v_lshl_add_u64 v[134:135], v[134:135], 0, v[132:133]
	v_cvt_pk_bf16_f32 v138, v138, v140
	v_cvt_pk_bf16_f32 v140, v143, v144
	v_cvt_pk_bf16_f32 v141, v145, v146
	v_add_co_u32_e32 v134, vcc, s72, v134
	v_permlane16_swap_b32_e32 v138, v140
	v_permlane16_swap_b32_e32 v139, v141
	v_addc_co_u32_e32 v135, vcc, 0, v135, vcc
	v_mul_f32_e32 v137, 0xbfb8aa3b, v52
	global_store_dwordx4 v[134:135], v[138:141], off
	v_mul_f32_e32 v143, 0xbfb8aa3b, v50
	v_mul_f32_e32 v144, 0xbfb8aa3b, v51
	v_add_f32_e32 v138, 1.0, v142
	v_mul_f32_e32 v139, 0xbfb8aa3b, v54
	v_mul_f32_e32 v140, 0xbfb8aa3b, v55
	v_mul_f32_e32 v141, 0xbfb8aa3b, v48
	v_mul_f32_e32 v142, 0xbfb8aa3b, v49
	v_exp_f32_e32 v137, v137
	v_exp_f32_e32 v139, v139
	v_exp_f32_e32 v140, v140
	v_exp_f32_e32 v141, v141
	v_exp_f32_e32 v142, v142
	v_exp_f32_e32 v143, v143
	v_exp_f32_e32 v144, v144
	v_add_f32_e32 v137, 1.0, v137
	v_add_f32_e32 v139, 1.0, v139
	v_add_f32_e32 v140, 1.0, v140
	v_add_f32_e32 v141, 1.0, v141
	v_add_f32_e32 v142, 1.0, v142
	v_add_f32_e32 v143, 1.0, v143
	v_add_f32_e32 v144, 1.0, v144
	v_rcp_f32_e32 v137, v137
	v_rcp_f32_e32 v138, v138
	v_rcp_f32_e32 v139, v139
	v_rcp_f32_e32 v140, v140
	v_rcp_f32_e32 v141, v141
	v_rcp_f32_e32 v142, v142
	v_rcp_f32_e32 v143, v143
	v_rcp_f32_e32 v144, v144
	v_cvt_pk_bf16_f32 v138, v137, v138
	v_cvt_pk_bf16_f32 v139, v139, v140
	v_cvt_pk_bf16_f32 v140, v141, v142
	v_cvt_pk_bf16_f32 v141, v143, v144
	s_nop 0
	v_permlane16_swap_b32_e32 v138, v140
	v_permlane16_swap_b32_e32 v139, v141
; __device__ __forceinline__ u32x2 pack4(f32x4 v) { u32x2 r; r.x = cvt_pk(v[0], v[1]); r.y = cvt_pk(v[2], v[3]); return r; }
; __device__ __forceinline__ float sigm_f(float x) { return __builtin_amdgcn_rcpf(1.f + __builtin_amdgcn_exp2f(-1.4426950409f * x)); }
; __device__ __forceinline__ void store_pair16(u16* rowp32, u32x2 a, u32x2 b, int fq) {
;   auto rx = __builtin_amdgcn_permlane16_swap(a.x, b.x, false, false);
;   auto ry = __builtin_amdgcn_permlane16_swap(a.y, b.y, false, false);
;   u32x4 w = {rx[0], ry[0], rx[1], ry[1]};
;   *(u32x4*)(rowp32 + ((fq & 1) * 16 + (fq >> 1) * 8)) = w;
; template <int SEC> __device__ __forceinline__ void epiB2(const Params& p, int row, int col32, f32x4 v0, f32x4 v1, int fq) {
;     ...
;   else { f32x4 o0 = {sigm_f(v0[0]), sigm_f(v0[1]), sigm_f(v0[2]), sigm_f(v0[3])}, o1 = {sigm_f(v1[0]), sigm_f(v1[1]), sigm_f(v1[2]), sigm_f(v1[3])};
;     store_pair16((u16*)(ws + OFF_GATE) + (size_t)row * 3072 + (col32 - 4096), pack4(o0), pack4(o1), fq); }
	global_store_dwordx4 v[134:135], v[138:141], off offset:256
	v_mul_f32_e32 v134, 0xbfb8aa3b, v44
	v_exp_f32_e32 v134, v134
	v_mul_f32_e32 v135, 0xbfb8aa3b, v45
	v_exp_f32_e32 v135, v135
	v_mul_f32_e32 v139, 0xbfb8aa3b, v47
	v_add_f32_e32 v134, 1.0, v134
	v_rcp_f32_e32 v138, v134
	v_add_f32_e32 v134, 1.0, v135
	v_mul_f32_e32 v135, 0xbfb8aa3b, v46
	v_exp_f32_e32 v135, v135
	v_exp_f32_e32 v139, v139
	v_rcp_f32_e32 v140, v134
	v_add_u32_e32 v137, 0x90, v128
	v_add_f32_e32 v134, 1.0, v135
	v_mul_f32_e32 v135, 0xbfb8aa3b, v40
	v_rcp_f32_e32 v141, v134
	v_add_f32_e32 v134, 1.0, v139
	v_exp_f32_e32 v135, v135
	v_mul_f32_e32 v139, 0xbfb8aa3b, v41
	v_exp_f32_e32 v139, v139
	v_rcp_f32_e32 v142, v134
	v_add_f32_e32 v134, 1.0, v135
	v_mul_f32_e32 v135, 0xbfb8aa3b, v42
	v_rcp_f32_e32 v143, v134
	v_add_f32_e32 v134, 1.0, v139
	v_exp_f32_e32 v135, v135
	v_mul_f32_e32 v139, 0xbfb8aa3b, v43
	v_exp_f32_e32 v139, v139
	v_rcp_f32_e32 v144, v134
	v_add_f32_e32 v134, 1.0, v135
	v_rcp_f32_e32 v145, v134
	v_add_f32_e32 v134, 1.0, v139
	v_rcp_f32_e32 v146, v134
	v_mad_u64_u32 v[134:135], s[40:41], v137, s71, v[130:131]
	v_cvt_pk_bf16_f32 v139, v141, v142
	v_mul_f32_e32 v142, 0xbfb8aa3b, v37
	v_lshl_add_u64 v[134:135], v[134:135], 0, s[4:5]
	v_exp_f32_e32 v142, v142
	v_lshl_add_u64 v[134:135], v[134:135], 0, v[132:133]
	v_cvt_pk_bf16_f32 v138, v138, v140
	v_cvt_pk_bf16_f32 v140, v143, v144
	v_cvt_pk_bf16_f32 v141, v145, v146
	v_add_co_u32_e32 v134, vcc, s72, v134
	v_permlane16_swap_b32_e32 v138, v140
	v_permlane16_swap_b32_e32 v139, v141
	v_addc_co_u32_e32 v135, vcc, 0, v135, vcc
	v_mul_f32_e32 v137, 0xbfb8aa3b, v36
	global_store_dwordx4 v[134:135], v[138:141], off
	v_mul_f32_e32 v143, 0xbfb8aa3b, v34
	v_mul_f32_e32 v144, 0xbfb8aa3b, v35
	v_add_f32_e32 v138, 1.0, v142
	v_mul_f32_e32 v139, 0xbfb8aa3b, v38
	v_mul_f32_e32 v140, 0xbfb8aa3b, v39
	v_mul_f32_e32 v141, 0xbfb8aa3b, v32
	v_mul_f32_e32 v142, 0xbfb8aa3b, v33
	v_exp_f32_e32 v137, v137
	v_exp_f32_e32 v139, v139
	v_exp_f32_e32 v140, v140
	v_exp_f32_e32 v141, v141
	v_exp_f32_e32 v142, v142
	v_exp_f32_e32 v143, v143
	v_exp_f32_e32 v144, v144
	v_add_f32_e32 v137, 1.0, v137
	v_add_f32_e32 v139, 1.0, v139
	v_add_f32_e32 v140, 1.0, v140
	v_add_f32_e32 v141, 1.0, v141
	v_add_f32_e32 v142, 1.0, v142
	v_add_f32_e32 v143, 1.0, v143
	v_add_f32_e32 v144, 1.0, v144
	v_rcp_f32_e32 v137, v137
	v_rcp_f32_e32 v138, v138
	v_rcp_f32_e32 v139, v139
	v_rcp_f32_e32 v140, v140
	v_rcp_f32_e32 v141, v141
	v_rcp_f32_e32 v142, v142
	v_rcp_f32_e32 v143, v143
	v_rcp_f32_e32 v144, v144
	v_cvt_pk_bf16_f32 v138, v137, v138
	v_cvt_pk_bf16_f32 v139, v139, v140
	v_cvt_pk_bf16_f32 v140, v141, v142
	v_cvt_pk_bf16_f32 v141, v143, v144
	s_nop 0
	v_permlane16_swap_b32_e32 v138, v140
	v_permlane16_swap_b32_e32 v139, v141
	global_store_dwordx4 v[134:135], v[138:141], off offset:256
	v_mul_f32_e32 v134, 0xbfb8aa3b, v28
	v_exp_f32_e32 v134, v134
	v_mul_f32_e32 v135, 0xbfb8aa3b, v29
	v_exp_f32_e32 v135, v135
	v_mul_f32_e32 v139, 0xbfb8aa3b, v31
	v_add_f32_e32 v134, 1.0, v134
	v_rcp_f32_e32 v138, v134
	v_add_f32_e32 v134, 1.0, v135
	v_mul_f32_e32 v135, 0xbfb8aa3b, v30
	v_exp_f32_e32 v135, v135
	v_exp_f32_e32 v139, v139
	v_rcp_f32_e32 v140, v134
	v_add_u32_e32 v137, 0xa0, v128
	v_add_f32_e32 v134, 1.0, v135
	v_mul_f32_e32 v135, 0xbfb8aa3b, v24
	v_rcp_f32_e32 v141, v134
	v_add_f32_e32 v134, 1.0, v139
	v_exp_f32_e32 v135, v135
	v_mul_f32_e32 v139, 0xbfb8aa3b, v25
	v_exp_f32_e32 v139, v139
	v_rcp_f32_e32 v142, v134
	v_add_f32_e32 v134, 1.0, v135
	v_mul_f32_e32 v135, 0xbfb8aa3b, v26
	v_rcp_f32_e32 v143, v134
	v_add_f32_e32 v134, 1.0, v139
	v_exp_f32_e32 v135, v135
	v_mul_f32_e32 v139, 0xbfb8aa3b, v27
	v_exp_f32_e32 v139, v139
	v_rcp_f32_e32 v144, v134
	v_add_f32_e32 v134, 1.0, v135
	v_rcp_f32_e32 v145, v134
	v_add_f32_e32 v134, 1.0, v139
	v_rcp_f32_e32 v146, v134
	v_mad_u64_u32 v[134:135], s[40:41], v137, s71, v[130:131]
	v_cvt_pk_bf16_f32 v139, v141, v142
	v_mul_f32_e32 v142, 0xbfb8aa3b, v21
	v_lshl_add_u64 v[134:135], v[134:135], 0, s[4:5]
	v_exp_f32_e32 v142, v142
	v_lshl_add_u64 v[134:135], v[134:135], 0, v[132:133]
	v_cvt_pk_bf16_f32 v138, v138, v140
	v_cvt_pk_bf16_f32 v140, v143, v144
	v_cvt_pk_bf16_f32 v141, v145, v146
; __device__ __forceinline__ u32x2 pack4(f32x4 v) { u32x2 r; r.x = cvt_pk(v[0], v[1]); r.y = cvt_pk(v[2], v[3]); return r; }
; __device__ __forceinline__ float sigm_f(float x) { return __builtin_amdgcn_rcpf(1.f + __builtin_amdgcn_exp2f(-1.4426950409f * x)); }
; __device__ __forceinline__ void store_pair16(u16* rowp32, u32x2 a, u32x2 b, int fq) {
;   auto rx = __builtin_amdgcn_permlane16_swap(a.x, b.x, false, false);
;   auto ry = __builtin_amdgcn_permlane16_swap(a.y, b.y, false, false);
;   u32x4 w = {rx[0], ry[0], rx[1], ry[1]};
;   *(u32x4*)(rowp32 + ((fq & 1) * 16 + (fq >> 1) * 8)) = w;
; template <int SEC> __device__ __forceinline__ void epiB2(const Params& p, int row, int col32, f32x4 v0, f32x4 v1, int fq) {
;     ...
;   else { f32x4 o0 = {sigm_f(v0[0]), sigm_f(v0[1]), sigm_f(v0[2]), sigm_f(v0[3])}, o1 = {sigm_f(v1[0]), sigm_f(v1[1]), sigm_f(v1[2]), sigm_f(v1[3])};
;     store_pair16((u16*)(ws + OFF_GATE) + (size_t)row * 3072 + (col32 - 4096), pack4(o0), pack4(o1), fq); }
	v_add_co_u32_e32 v134, vcc, s72, v134
	v_permlane16_swap_b32_e32 v138, v140
	v_permlane16_swap_b32_e32 v139, v141
	v_addc_co_u32_e32 v135, vcc, 0, v135, vcc
	v_mul_f32_e32 v137, 0xbfb8aa3b, v20
	global_store_dwordx4 v[134:135], v[138:141], off
	v_mul_f32_e32 v143, 0xbfb8aa3b, v18
	v_mul_f32_e32 v144, 0xbfb8aa3b, v19
	v_add_f32_e32 v138, 1.0, v142
	v_mul_f32_e32 v139, 0xbfb8aa3b, v22
	v_mul_f32_e32 v140, 0xbfb8aa3b, v23
	v_mul_f32_e32 v141, 0xbfb8aa3b, v16
	v_mul_f32_e32 v142, 0xbfb8aa3b, v17
	v_exp_f32_e32 v137, v137
	v_exp_f32_e32 v139, v139
	v_exp_f32_e32 v140, v140
	v_exp_f32_e32 v141, v141
	v_exp_f32_e32 v142, v142
	v_exp_f32_e32 v143, v143
	v_exp_f32_e32 v144, v144
	v_add_f32_e32 v137, 1.0, v137
	v_add_f32_e32 v139, 1.0, v139
	v_add_f32_e32 v140, 1.0, v140
	v_add_f32_e32 v141, 1.0, v141
	v_add_f32_e32 v142, 1.0, v142
	v_add_f32_e32 v143, 1.0, v143
	v_add_f32_e32 v144, 1.0, v144
	v_rcp_f32_e32 v137, v137
	v_rcp_f32_e32 v138, v138
	v_rcp_f32_e32 v139, v139
	v_rcp_f32_e32 v140, v140
	v_rcp_f32_e32 v141, v141
	v_rcp_f32_e32 v142, v142
	v_rcp_f32_e32 v143, v143
	v_rcp_f32_e32 v144, v144
	v_cvt_pk_bf16_f32 v138, v137, v138
	v_cvt_pk_bf16_f32 v139, v139, v140
	v_cvt_pk_bf16_f32 v140, v141, v142
	v_cvt_pk_bf16_f32 v141, v143, v144
	s_nop 0
	v_permlane16_swap_b32_e32 v138, v140
	v_permlane16_swap_b32_e32 v139, v141
	global_store_dwordx4 v[134:135], v[138:141], off offset:256
	v_mul_f32_e32 v134, 0xbfb8aa3b, v12
	v_mul_f32_e32 v135, 0xbfb8aa3b, v13
	v_mul_f32_e32 v138, 0xbfb8aa3b, v15
	v_exp_f32_e32 v138, v138
	v_mul_f32_e32 v139, 0xbfb8aa3b, v8
	v_exp_f32_e32 v139, v139
	v_mul_f32_e32 v140, 0xbfb8aa3b, v9
	v_exp_f32_e32 v140, v140
	v_add_f32_e32 v138, 1.0, v138
	v_rcp_f32_e32 v141, v138
	v_add_f32_e32 v138, 1.0, v139
	v_mul_f32_e32 v139, 0xbfb8aa3b, v10
	v_mul_f32_e32 v137, 0xbfb8aa3b, v14
	v_rcp_f32_e32 v142, v138
	v_add_f32_e32 v138, 1.0, v140
	v_exp_f32_e32 v139, v139
	v_mul_f32_e32 v140, 0xbfb8aa3b, v11
	v_exp_f32_e32 v134, v134
	v_exp_f32_e32 v135, v135
	v_exp_f32_e32 v137, v137
	v_exp_f32_e32 v140, v140
	v_rcp_f32_e32 v143, v138
	v_add_f32_e32 v138, 1.0, v139
	v_add_f32_e32 v134, 1.0, v134
	v_add_f32_e32 v135, 1.0, v135
	v_add_f32_e32 v137, 1.0, v137
	v_rcp_f32_e32 v144, v138
	v_add_f32_e32 v138, 1.0, v140
	v_add_u32_e32 v128, 0xb0, v128
	v_rcp_f32_e32 v134, v134
	v_rcp_f32_e32 v135, v135
	v_rcp_f32_e32 v137, v137
	v_rcp_f32_e32 v145, v138
	v_mad_u64_u32 v[130:131], s[40:41], v128, s71, v[130:131]
	v_lshl_add_u64 v[130:131], v[130:131], 0, s[4:5]
	v_lshl_add_u64 v[130:131], v[130:131], 0, v[132:133]
	v_cvt_pk_bf16_f32 v138, v134, v135
	v_cvt_pk_bf16_f32 v139, v137, v141
	v_cvt_pk_bf16_f32 v140, v142, v143
	v_cvt_pk_bf16_f32 v141, v144, v145
	v_add_co_u32_e32 v134, vcc, s72, v130
	v_permlane16_swap_b32_e32 v138, v140
	v_permlane16_swap_b32_e32 v139, v141
	v_addc_co_u32_e32 v135, vcc, 0, v131, vcc
	v_mul_f32_e32 v128, 0xbfb8aa3b, v4
	v_mul_f32_e32 v130, 0xbfb8aa3b, v5
	global_store_dwordx4 v[134:135], v[138:141], off
	v_mul_f32_e32 v131, 0xbfb8aa3b, v6
	v_mul_f32_e32 v132, 0xbfb8aa3b, v7
	v_mul_f32_e32 v133, 0xbfb8aa3b, v0
	v_mul_f32_e32 v137, 0xbfb8aa3b, v1
	v_mul_f32_e32 v138, 0xbfb8aa3b, v2
	v_mul_f32_e32 v139, 0xbfb8aa3b, v3
	v_exp_f32_e32 v128, v128
	v_exp_f32_e32 v130, v130
	v_exp_f32_e32 v131, v131
	v_exp_f32_e32 v132, v132
	v_exp_f32_e32 v133, v133
	v_exp_f32_e32 v137, v137
	v_exp_f32_e32 v138, v138
	v_exp_f32_e32 v139, v139
	v_add_f32_e32 v128, 1.0, v128
	v_add_f32_e32 v130, 1.0, v130
	v_add_f32_e32 v131, 1.0, v131
	v_add_f32_e32 v132, 1.0, v132
	v_add_f32_e32 v133, 1.0, v133
	v_add_f32_e32 v137, 1.0, v137
	v_add_f32_e32 v138, 1.0, v138
	v_add_f32_e32 v139, 1.0, v139
	v_rcp_f32_e32 v128, v128
	v_rcp_f32_e32 v130, v130
	v_rcp_f32_e32 v131, v131
	v_rcp_f32_e32 v132, v132
	v_rcp_f32_e32 v133, v133
	v_rcp_f32_e32 v137, v137
	v_rcp_f32_e32 v138, v138
	v_rcp_f32_e32 v139, v139
	v_cvt_pk_bf16_f32 v130, v128, v130
	v_cvt_pk_bf16_f32 v131, v131, v132
	v_cvt_pk_bf16_f32 v132, v133, v137
	v_cvt_pk_bf16_f32 v133, v138, v139
	s_nop 0
	v_permlane16_swap_b32_e32 v130, v132
	v_permlane16_swap_b32_e32 v131, v133
	global_store_dwordx4 v[134:135], v[130:133], off offset:256
	s_mov_b64 s[4:5], 0

; __device__ __forceinline__ int lane_fresh() { int l; asm volatile("v_mbcnt_lo_u32_b32 %0, -1, 0\n\tv_mbcnt_hi_u32_b32 %0, -1, %0" : "=v"(l)); return l; }
; #define MFMA16(a, b, c) __builtin_amdgcn_mfma_f32_16x16x32_bf16((a), (b), (c), 0, 0, 0)
; template <int NT, class FA, class FB, class FL>
; __device__ __forceinline__ void skgemm(FA aptr, FB bptr, FL ldf, const int KS, const int wv) {
;   float* part = (float*)g_shm;
;   const int lane = lane_fresh(), fr = lane & 15, fq = lane >> 4;
;   __syncthreads();
; #pragma unroll
;   for (int i = 0; i < NT; ++i) {
;     f32x4 acc = {0.f, 0.f, 0.f, 0.f};
;     const int ld = ldf(i);
;     const u16* ap = aptr(i) + (size_t)fr * ld + wv * KS + fq * 8;
;     const u16* bp = bptr(i) + (size_t)fr * ld + wv * KS + fq * 8;
; #pragma unroll 8
;     for (int k = 0; k < KS; k += 32) acc = MFMA16(*(const bf16x8*)(bp + k), *(const bf16x8*)(ap + k), acc);
;     *(f32x4*)(part + ((i * 8 + wv) * 64 + lane) * 4) = acc;
; __device__ __forceinline__ void phaseB(const Params& p, const int wv, const int rep) {
;     ...
;   for (int gb = blockIdx.x; gb < 256; gb += gridDim.x) {
;     const int task0 = gb * 14, mt = task0 / 448, nt0 = task0 - mt * 448;
;     const u16* Ab = XN + (size_t)(TP + mt * 16) * 1024;
;     const u16* Bb = (const u16*)(ws + OFF_WIN) + (size_t)(nt0 * 16) * 1024;
;     skgemm<14>([&](int) { return Ab; }, [&](int i) { return Bb + (size_t)i * 16 * 1024; }, [&](int) { return 1024; }, 128, wv);
.LBB0_225:
	s_ashr_i32 s23, s43, 31
	s_lshr_b32 s23, s23, 27
	s_add_i32 s23, s43, s23
	s_ashr_i32 s26, s23, 5
	s_mul_i32 s22, s43, 14
	s_mul_i32 s23, s26, 0xfffffe40
	s_add_i32 s27, s23, s22
	s_lshl_b32 s22, s26, 4
	s_addk_i32 s22, 0x4000
	s_ashr_i32 s23, s22, 31
	s_lshl_b64 s[24:25], s[22:23], 11
	s_add_u32 s24, s48, s24
	s_addc_u32 s25, s49, s25
	s_lshl_b32 s28, s27, 4
	s_ashr_i32 s29, s28, 31
	v_mbcnt_lo_u32_b32 v56, -1, 0
	v_mbcnt_hi_u32_b32 v56, -1, v56
	s_lshl_b64 s[28:29], s[28:29], 11
	v_ashrrev_i32_e32 v0, 1, v56
	v_lshlrev_b32_e32 v2, 11, v56
	v_and_b32_e32 v0, -8, v0
	v_and_b32_e32 v52, 0x7800, v2
	s_add_u32 s28, s50, s28
	v_ashrrev_i32_e32 v1, 31, v0
	v_lshl_add_u64 v[2:3], s[24:25], 0, v[52:53]
	s_addc_u32 s29, s51, s29
	v_lshl_add_u64 v[2:3], v[2:3], 0, s[0:1]
	v_lshlrev_b64 v[0:1], 1, v[0:1]
	v_lshl_add_u64 v[86:87], v[2:3], 0, v[0:1]
	v_lshl_add_u64 v[2:3], s[28:29], 0, v[52:53]
	v_lshl_add_u64 v[2:3], v[2:3], 0, s[0:1]
	v_lshl_add_u64 v[54:55], v[2:3], 0, v[0:1]
	s_mov_b32 s23, 0x8000
	v_add_co_u32_e32 v8, vcc, s23, v54
	s_mov_b32 s23, 0x10000
	s_nop 0
	v_addc_co_u32_e32 v9, vcc, 0, v55, vcc
	s_waitcnt lgkmcnt(0)
	s_barrier
	s_lshr_b32 s23, s43, 6
	s_lshl_b32 s23, s23, 5
	s_addk_i32 s23, 0x4000
	s_lshl_b32 s24, s23, 11
	s_add_u32 s24, s48, s24
	s_addc_u32 s25, s49, 0
	s_and_b32 s27, s43, 63
	s_mul_i32 s27, s27, 7
	s_lshl_b32 s27, s27, 15
	s_add_u32 s28, s50, s27
	s_addc_u32 s29, s51, 0
	v_and_b32_e32 v248, 15, v56
	v_lshlrev_b32_e32 v248, 11, v248
	v_lshrrev_b32_e32 v249, 4, v56
	v_lshl_add_u32 v248, v249, 4, v248
	v_add_u32_e32 v248, s0, v248
	v_lshlrev_b32_e32 v249, 4, v56
	v_add_u32_e32 v249, s13, v249
	v_add_u32_e32 v62, 0x10000, v249
	v_readlane_b32 s23, v251, 1
	s_nop 3
	s_cmp_eq_u32 s23, 0x100
	s_cbranch_scc1 .Lsk3_have
	global_load_dwordx4 v[150:153], v248, s[24:25]
	global_load_dwordx4 v[154:157], v248, s[24:25] offset:64
	global_load_dwordx4 v[158:161], v248, s[24:25] offset:128
	global_load_dwordx4 v[162:165], v248, s[24:25] offset:192
	s_add_u32 s24, s24, 0x8000
	s_addc_u32 s25, s25, 0
	global_load_dwordx4 v[166:169], v248, s[24:25]
	global_load_dwordx4 v[170:173], v248, s[24:25] offset:64
	global_load_dwordx4 v[174:177], v248, s[24:25] offset:128
	global_load_dwordx4 v[178:181], v248, s[24:25] offset:192
	global_load_dwordx4 v[182:185], v248, s[28:29]
	global_load_dwordx4 v[186:189], v248, s[28:29] offset:64
	global_load_dwordx4 v[190:193], v248, s[28:29] offset:128
	global_load_dwordx4 v[194:197], v248, s[28:29] offset:192
	s_add_u32 s28, s28, 0x8000
	s_addc_u32 s29, s29, 0
	global_load_dwordx4 v[198:201], v248, s[28:29]
	global_load_dwordx4 v[202:205], v248, s[28:29] offset:64
	global_load_dwordx4 v[206:209], v248, s[28:29] offset:128
	global_load_dwordx4 v[210:213], v248, s[28:29] offset:192
	s_add_u32 s28, s28, 0x8000
	s_addc_u32 s29, s29, 0
	global_load_dwordx4 v[214:217], v248, s[28:29]
	global_load_dwordx4 v[218:221], v248, s[28:29] offset:64
	global_load_dwordx4 v[222:225], v248, s[28:29] offset:128
	global_load_dwordx4 v[226:229], v248, s[28:29] offset:192
	s_add_u32 s28, s28, 0x8000
	s_addc_u32 s29, s29, 0
	global_load_dwordx4 v[230:233], v248, s[28:29]
	global_load_dwordx4 v[234:237], v248, s[28:29] offset:64
	global_load_dwordx4 v[238:241], v248, s[28:29] offset:128
	global_load_dwordx4 v[242:245], v248, s[28:29] offset:192
	s_add_u32 s28, s28, 0x8000
	s_addc_u32 s29, s29, 0
	s_branch .Lsk3_rest
.Lsk3_have:
	s_add_u32 s28, s28, 0x20000
	s_addc_u32 s29, s29, 0
; #define MFMA16(a, b, c) __builtin_amdgcn_mfma_f32_16x16x32_bf16((a), (b), (c), 0, 0, 0)
; template <int NT, class FA, class FB, class FL>
; __device__ __forceinline__ void skgemm(FA aptr, FB bptr, FL ldf, const int KS, const int wv) {
;     ...
;   for (int i = 0; i < NT; ++i) {
;     f32x4 acc = {0.f, 0.f, 0.f, 0.f};
;     const int ld = ldf(i);
;     const u16* ap = aptr(i) + (size_t)fr * ld + wv * KS + fq * 8;
;     const u16* bp = bptr(i) + (size_t)fr * ld + wv * KS + fq * 8;
; #pragma unroll 8
;     for (int k = 0; k < KS; k += 32) acc = MFMA16(*(const bf16x8*)(bp + k), *(const bf16x8*)(ap + k), acc);
;     *(f32x4*)(part + ((i * 8 + wv) * 64 + lane) * 4) = acc;
;   }
;   __syncthreads();
.Lsk3_rest:
	global_load_dwordx4 v[64:67], v248, s[28:29]
	global_load_dwordx4 v[68:71], v248, s[28:29] offset:64
	global_load_dwordx4 v[72:75], v248, s[28:29] offset:128
	global_load_dwordx4 v[76:79], v248, s[28:29] offset:192
	s_add_u32 s28, s28, 0x8000
	s_addc_u32 s29, s29, 0
	global_load_dwordx4 v[80:83], v248, s[28:29]
	global_load_dwordx4 v[84:87], v248, s[28:29] offset:64
	global_load_dwordx4 v[88:91], v248, s[28:29] offset:128
	global_load_dwordx4 v[92:95], v248, s[28:29] offset:192
	s_add_u32 s28, s28, 0x8000
	s_addc_u32 s29, s29, 0
	global_load_dwordx4 v[96:99], v248, s[28:29]
	global_load_dwordx4 v[100:103], v248, s[28:29] offset:64
	global_load_dwordx4 v[104:107], v248, s[28:29] offset:128
	global_load_dwordx4 v[108:111], v248, s[28:29] offset:192
	s_add_u32 s28, s28, 0x8000
	s_addc_u32 s29, s29, 0
	s_waitcnt vmcnt(12)
	v_mfma_f32_16x16x32_bf16 v[112:115], v[182:185], v[150:153], 0
	v_mfma_f32_16x16x32_bf16 v[112:115], v[186:189], v[154:157], v[112:115]
	v_mfma_f32_16x16x32_bf16 v[112:115], v[190:193], v[158:161], v[112:115]
	v_mfma_f32_16x16x32_bf16 v[112:115], v[194:197], v[162:165], v[112:115]
	v_mfma_f32_16x16x32_bf16 v[116:119], v[198:201], v[150:153], 0
	v_mfma_f32_16x16x32_bf16 v[116:119], v[202:205], v[154:157], v[116:119]
	v_mfma_f32_16x16x32_bf16 v[116:119], v[206:209], v[158:161], v[116:119]
	v_mfma_f32_16x16x32_bf16 v[116:119], v[210:213], v[162:165], v[116:119]
	v_mfma_f32_16x16x32_bf16 v[120:123], v[214:217], v[150:153], 0
	v_mfma_f32_16x16x32_bf16 v[120:123], v[218:221], v[154:157], v[120:123]
	v_mfma_f32_16x16x32_bf16 v[120:123], v[222:225], v[158:161], v[120:123]
	v_mfma_f32_16x16x32_bf16 v[120:123], v[226:229], v[162:165], v[120:123]
	s_nop 1
	ds_write_b128 v249, v[112:115]
	v_mfma_f32_16x16x32_bf16 v[124:127], v[230:233], v[150:153], 0
	v_mfma_f32_16x16x32_bf16 v[124:127], v[234:237], v[154:157], v[124:127]
	v_mfma_f32_16x16x32_bf16 v[124:127], v[238:241], v[158:161], v[124:127]
	v_mfma_f32_16x16x32_bf16 v[124:127], v[242:245], v[162:165], v[124:127]
	s_nop 1
	ds_write_b128 v249, v[116:119] offset:8192
	v_mfma_f32_16x16x32_bf16 v[140:143], v[182:185], v[166:169], 0
	v_mfma_f32_16x16x32_bf16 v[140:143], v[186:189], v[170:173], v[140:143]
	v_mfma_f32_16x16x32_bf16 v[140:143], v[190:193], v[174:177], v[140:143]
	v_mfma_f32_16x16x32_bf16 v[140:143], v[194:197], v[178:181], v[140:143]
	s_nop 1
	ds_write_b128 v249, v[120:123] offset:16384
	v_mfma_f32_16x16x32_bf16 v[144:147], v[198:201], v[166:169], 0
	v_mfma_f32_16x16x32_bf16 v[144:147], v[202:205], v[170:173], v[144:147]
	v_mfma_f32_16x16x32_bf16 v[144:147], v[206:209], v[174:177], v[144:147]
	v_mfma_f32_16x16x32_bf16 v[144:147], v[210:213], v[178:181], v[144:147]
	s_nop 1
	ds_write_b128 v249, v[124:127] offset:24576
	v_mfma_f32_16x16x32_bf16 v[0:3], v[214:217], v[166:169], 0
	v_mfma_f32_16x16x32_bf16 v[0:3], v[218:221], v[170:173], v[0:3]
	v_mfma_f32_16x16x32_bf16 v[0:3], v[222:225], v[174:177], v[0:3]
	v_mfma_f32_16x16x32_bf16 v[0:3], v[226:229], v[178:181], v[0:3]
	s_nop 1
	ds_write_b128 v249, v[140:143] offset:57344
	v_mfma_f32_16x16x32_bf16 v[4:7], v[230:233], v[166:169], 0
	v_mfma_f32_16x16x32_bf16 v[4:7], v[234:237], v[170:173], v[4:7]
	v_mfma_f32_16x16x32_bf16 v[4:7], v[238:241], v[174:177], v[4:7]
	v_mfma_f32_16x16x32_bf16 v[4:7], v[242:245], v[178:181], v[4:7]
	s_nop 1
	ds_write_b128 v62, v[144:147]
	s_waitcnt vmcnt(11)
	v_mfma_f32_16x16x32_bf16 v[128:131], v[64:67], v[150:153], 0
	s_waitcnt vmcnt(10)
	v_mfma_f32_16x16x32_bf16 v[128:131], v[68:71], v[154:157], v[128:131]
	s_waitcnt vmcnt(9)
	v_mfma_f32_16x16x32_bf16 v[128:131], v[72:75], v[158:161], v[128:131]
	s_waitcnt vmcnt(8)
	v_mfma_f32_16x16x32_bf16 v[128:131], v[76:79], v[162:165], v[128:131]
	s_nop 1
	ds_write_b128 v62, v[0:3] offset:8192
	s_waitcnt vmcnt(7)
	v_mfma_f32_16x16x32_bf16 v[132:135], v[80:83], v[150:153], 0
	s_waitcnt vmcnt(6)
	v_mfma_f32_16x16x32_bf16 v[132:135], v[84:87], v[154:157], v[132:135]
	s_waitcnt vmcnt(5)
	v_mfma_f32_16x16x32_bf16 v[132:135], v[88:91], v[158:161], v[132:135]
	s_waitcnt vmcnt(4)
	v_mfma_f32_16x16x32_bf16 v[132:135], v[92:95], v[162:165], v[132:135]
	s_nop 1
	ds_write_b128 v62, v[4:7] offset:16384
	s_waitcnt vmcnt(3)
	v_mfma_f32_16x16x32_bf16 v[136:139], v[96:99], v[150:153], 0
	s_waitcnt vmcnt(2)
	v_mfma_f32_16x16x32_bf16 v[136:139], v[100:103], v[154:157], v[136:139]
	s_waitcnt vmcnt(1)
	v_mfma_f32_16x16x32_bf16 v[136:139], v[104:107], v[158:161], v[136:139]
	s_waitcnt vmcnt(0)
	v_mfma_f32_16x16x32_bf16 v[136:139], v[108:111], v[162:165], v[136:139]
	s_nop 1
	ds_write_b128 v249, v[128:131] offset:32768
	s_waitcnt vmcnt(11)
	v_mfma_f32_16x16x32_bf16 v[8:11], v[64:67], v[166:169], 0
	s_waitcnt vmcnt(10)
	v_mfma_f32_16x16x32_bf16 v[8:11], v[68:71], v[170:173], v[8:11]
	s_waitcnt vmcnt(9)
	v_mfma_f32_16x16x32_bf16 v[8:11], v[72:75], v[174:177], v[8:11]
	s_waitcnt vmcnt(8)
	v_mfma_f32_16x16x32_bf16 v[8:11], v[76:79], v[178:181], v[8:11]
	s_nop 1
	ds_write_b128 v249, v[132:135] offset:40960
	s_waitcnt vmcnt(7)
	v_mfma_f32_16x16x32_bf16 v[12:15], v[80:83], v[166:169], 0
	s_waitcnt vmcnt(6)
	v_mfma_f32_16x16x32_bf16 v[12:15], v[84:87], v[170:173], v[12:15]
	s_waitcnt vmcnt(5)
	v_mfma_f32_16x16x32_bf16 v[12:15], v[88:91], v[174:177], v[12:15]
	s_waitcnt vmcnt(4)
	v_mfma_f32_16x16x32_bf16 v[12:15], v[92:95], v[178:181], v[12:15]
	s_nop 1
	ds_write_b128 v249, v[136:139] offset:49152
	s_waitcnt vmcnt(3)
	v_mfma_f32_16x16x32_bf16 v[16:19], v[96:99], v[166:169], 0
	s_waitcnt vmcnt(2)
	v_mfma_f32_16x16x32_bf16 v[16:19], v[100:103], v[170:173], v[16:19]
	s_waitcnt vmcnt(1)
	v_mfma_f32_16x16x32_bf16 v[16:19], v[104:107], v[174:177], v[16:19]
	s_waitcnt vmcnt(0)
	v_mfma_f32_16x16x32_bf16 v[16:19], v[108:111], v[178:181], v[16:19]
	s_nop 1
	ds_write_b128 v62, v[8:11] offset:24576
	s_andn2_b64 vcc, exec, s[4:5]
	s_nop 7
	ds_write_b128 v62, v[12:15] offset:32768
	ds_write_b128 v62, v[16:19] offset:40960
	s_waitcnt lgkmcnt(0)
	s_barrier
	s_cbranch_vccnz .LBB0_224
	s_ashr_i32 s23, s22, 11
	s_mul_hi_i32 s25, s23, 0x4800
	s_mulk_i32 s23, 0x4800
	s_add_u32 s24, s48, s23
	s_addc_u32 s25, s49, s25
	s_mul_i32 s23, s26, 0xffffe400
	s_mov_b32 s44, s15
	s_mov_b32 s45, s40
	s_branch .LBB0_229
